# P0 transposer item order remapped so a WG's 8 waves write 8 adjacent 128-B k-segments of the same 32 rows (1 KB contiguous per output row); on top of h1pf
# baseline (speedup 1.0000x reference)
; #define LAS __attribute__((address_space(3)))
; __device__ __forceinline__ void p0_prologue(const Ptrs& P, LAS unsigned char* lds, int vcu, int G, int tid) {
;     ...
;     constexpr int NITEMS = (D / 64) * (NIN / 32) + 2 * (HW / 64) * (D / 32) + (D / 64) * (D / 32);
;     if (gw < NITEMS) {
;         TItem cur = t_decode(P, gw, lane); f32x4 v[8]; t_load(cur, v);
; __device__ __forceinline__ Ptrs mkptrs(LAS const unsigned long long* pt) {
;     Ptrs P;
;     P.x = GP(const float, ldptr(pt, 0)); P.norm_w = GP(const float, ldptr(pt, 1)); P.w_in = GP(const float, ldptr(pt, 2)); P.lb_logits = GP(const float, ldptr(pt, 3)); P.hgrn_nw = GP(const float, ldptr(pt, 4));
;     P.conv_w = GP(const float, ldptr(pt, 5)); P.w_a = GP(const float, ldptr(pt, 6)); P.w_b = GP(const float, ldptr(pt, 7)); P.gate_bias = GP(const float, ldptr(pt, 8)); P.w_out = GP(const float, ldptr(pt, 9));
;     P.final_nw = GP(const float, ldptr(pt, 10)); P.out = GP(float, ldptr(pt, 11));
;     const unsigned long long ws = ldptr(pt, 12);
;     P.ssq = GP(float, ws + WS_SSQ); P.Dn = GP(float, ws + WS_DN);
;     P.W1T = GP(h16, ws + WS_W1T); P.WABT = GP(h16, ws + WS_WABT); P.WOT = GP(h16, ws + WS_WOT); P.U = GP(h16, ws + WS_U);
;     P.PA = GP(h16, ws + WS_PA); P.PG = GP(h16, ws + WS_PG); P.PP = GP(h16, ws + WS_PP); P.PGG = GP(h16, ws + WS_PGG);
;     P.YAB = GP(h16, ws + WS_YAB); P.L = GP(h16, ws + WS_L); P.S = GP(unsigned short, ws + WS_S); P.MG = GP(h16, ws + WS_MG); P.U8 = GP(unsigned char, ws + WS_U8); P.W8T = GP(unsigned char, ws + WS_W8T); P.cnt = GP(unsigned, ws + WS_CNT);
.LBB0_11:
	s_or_b64 exec, exec, s[0:1]
	s_add_i32 s0, 0, 0x24000
	v_mov_b32_e32 v2, s0
	s_waitcnt lgkmcnt(0)
	s_barrier
	ds_read_b128 v[2:5], v2
	s_lshl_b32 s1, s3, 3
	s_add_i32 s3, 0, 0x24010
	v_mov_b32_e32 v6, s3
	s_add_i32 s3, 0, 0x24030
	ds_read_b64 v[6:7], v6
	s_waitcnt lgkmcnt(1)
	v_readfirstlane_b32 s38, v2
	v_mov_b32_e32 v2, s3
	v_readfirstlane_b32 s31, v3
	v_readfirstlane_b32 s7, v5
	v_readfirstlane_b32 s6, v4
	ds_read_b128 v[2:5], v2
	s_add_i32 s3, 0, 0x24048
	s_waitcnt lgkmcnt(1)
	v_readfirstlane_b32 s10, v6
	v_mov_b32_e32 v6, s3
	s_add_i32 s3, 0, 0x24060
	v_readfirstlane_b32 s11, v7
	ds_read_b64 v[6:7], v6
	s_waitcnt lgkmcnt(1)
	v_readfirstlane_b32 s12, v2
	v_mov_b32_e32 v2, s3
	v_readfirstlane_b32 s13, v3
	ds_read_b64 v[2:3], v2
	v_mbcnt_lo_u32_b32 v36, -1, 0
	v_mbcnt_hi_u32_b32 v36, -1, v36
	s_lshl_b32 s0, s30, 3
	v_or_b32_e32 v90, s33, v36
	v_readfirstlane_b32 s15, v5
	v_readfirstlane_b32 s3, v90
	s_ashr_i32 s39, s3, 6
	s_add_i32 s3, s39, s1
	v_readfirstlane_b32 s14, v4
	s_waitcnt lgkmcnt(1)
	v_readfirstlane_b32 s17, v7
	v_readfirstlane_b32 s16, v6
	s_waitcnt lgkmcnt(0)
	v_readfirstlane_b32 s9, v3
	v_readfirstlane_b32 s8, v2
	s_cmp_lt_i32 s3, 0x10000
	v_and_b32_e32 v80, 63, v36
	s_cbranch_scc0 .LBB0_65
	s_mov_b32 s97, s3
	s_cmpk_gt_i32 s3, 0x3fff
	s_cbranch_scc1 .Lp0t_a_big
	s_and_b32 s94, s3, 7
	s_lshl_b32 s94, s94, 7
	s_bfe_u32 s95, s3, 0x70003
	s_and_b32 s3, s3, 0xfffffc00
	s_or_b32 s3, s3, s94
	s_or_b32 s3, s3, s95
	s_branch .Lp0t_a_done
.Lp0t_a_big:
	s_add_i32 s94, s3, 0xffffc000
	s_lshr_b32 s95, s94, 11
	s_mul_hi_u32 s95, s95, 0xaaaaaaab
	s_lshr_b32 s95, s95, 1
	s_mul_i32 s95, s95, 0x1800
	s_sub_i32 s94, s94, s95
	s_sub_i32 s3, s3, s94
	s_and_b32 s95, s94, 7
	s_mul_i32 s95, s95, 0x300
	s_lshr_b32 s94, s94, 3
	s_add_i32 s3, s3, s95
	s_add_i32 s3, s3, s94
.Lp0t_a_done:
	s_add_u32 s40, s8, 0x200000
	s_addc_u32 s41, s9, 0
	s_add_u32 s42, s8, 0xc200000
	s_addc_u32 s43, s9, 0
	s_add_u32 s44, s8, 0xe200000
	s_addc_u32 s45, s9, 0
	s_add_u32 s46, s8, 0x3a200000
	s_addc_u32 s47, s9, 0
	s_cmpk_gt_i32 s3, 0x3fff
	v_lshrrev_b32_e32 v81, 3, v80
	s_cbranch_scc0 .LBB0_15
	s_add_i32 s18, s3, 0xc000
	s_and_b32 s19, s18, 0xffff
	s_mul_i32 s19, s19, 0xaaab
	s_lshr_b32 s24, s19, 25
	s_mul_i32 s19, s24, 0x300
	s_sub_i32 s18, s18, s19
	s_and_b32 s22, s18, 0xffff
	s_lshl_b32 s23, s22, 5
	s_cmpk_gt_u32 s22, 0x1ff
	s_cselect_b64 s[18:19], -1, 0
	s_and_b64 vcc, exec, s[18:19]
	s_cbranch_vccz .LBB0_16
	v_lshlrev_b32_e32 v2, 3, v80
	s_lshl_b32 s20, s22, 10
	v_and_b32_e32 v2, 24, v2
	v_and_b32_e32 v3, 4, v36
	s_and_b32 s25, s23, 0x60
	s_and_b32 s20, s20, 0x1000
	s_lshl_b32 s21, s22, 4
	v_or3_b32 v2, v3, v2, s25
	s_and_b32 s21, s21, 0x3f80
	v_or_b32_e32 v2, s20, v2
	v_add_u32_e32 v2, s21, v2
	v_add_u32_e32 v2, 0x2000, v2
	s_cbranch_execz .LBB0_17
	s_branch .LBB0_21

; __device__ __forceinline__ void t_load(const TItem& t, f32x4 (&v)[8]) {
; #pragma unroll
;     for (int j = 0; j < 8; ++j) v[j] = __builtin_nontemporal_load((const f32x4*)(t.src + (size_t)(8 * j) * t.N));
; }
; __device__ __forceinline__ void p0_prologue(const Ptrs& P, LAS unsigned char* lds, int vcu, int G, int tid) {
;     ...
;         TItem cur = t_decode(P, gw, lane); f32x4 v[8]; t_load(cur, v);
;         for (int it = gw; it < NITEMS; it += NGW) {
;             const int nit = it + NGW; const bool has_n = nit < NITEMS;
;             f32x4 nv[8];
;             const TItem nxt = t_decode(P, has_n ? nit : it, lane); t_load(nxt, nv);
;             const int c4 = 4 * (lane & 7), r8 = lane >> 3;
.LBB0_36:
	s_lshl_b32 s20, s39, 14
	s_mov_b32 s21, 0
	s_add_i32 s24, s20, 0
	s_mul_i32 s20, s22, 0xe0
	v_lshl_add_u64 v[10:11], v[34:35], 0, s[20:21]
	s_lshl_b32 s20, s22, 5
	s_sub_u32 s22, 0, s20
	s_subb_u32 s23, 0, 0
	v_lshl_add_u64 v[12:13], v[10:11], 0, s[22:23]
	v_lshl_add_u64 v[18:19], v[12:13], 0, s[22:23]
	v_lshl_add_u64 v[20:21], v[18:19], 0, s[22:23]
	v_lshl_add_u64 v[26:27], v[20:21], 0, s[22:23]
	v_lshl_add_u64 v[28:29], v[26:27], 0, s[22:23]
	v_lshl_add_u64 v[38:39], v[28:29], 0, s[22:23]
	global_load_dwordx4 v[2:5], v[10:11], off nt
	global_load_dwordx4 v[6:9], v[12:13], off nt
	s_nop 0
	global_load_dwordx4 v[10:13], v[18:19], off nt
	global_load_dwordx4 v[14:17], v[20:21], off nt
	s_nop 0
	global_load_dwordx4 v[18:21], v[26:27], off nt
	global_load_dwordx4 v[22:25], v[28:29], off nt
	s_nop 0
	global_load_dwordx4 v[26:29], v[38:39], off nt
	global_load_dwordx4 v[30:33], v[34:35], off nt
	v_lshlrev_b32_e32 v34, 3, v80
	v_and_or_b32 v82, v34, 24, v37
	v_and_b32_e32 v34, 7, v36
	v_lshl_add_u32 v35, v34, 4, s24
	v_lshlrev_b32_e32 v66, 3, v34
	v_mul_u32_u24_e32 v34, 0x420, v34
	v_mov_b32_e32 v69, 0
	v_mul_u32_u24_e32 v36, 0x84, v81
	v_lshlrev_b32_e32 v37, 2, v81
	v_lshlrev_b32_e32 v70, 12, v81
	v_mov_b32_e32 v67, v69
	v_or_b32_e32 v83, 0x2000, v82
	v_add3_u32 v84, s24, v34, v37
	v_mov_b32_e32 v71, v69
	v_or_b32_e32 v72, 0x8000, v70
	v_mov_b32_e32 v73, v69
	v_or_b32_e32 v74, 0x10000, v70
	v_mov_b32_e32 v75, v69
	s_mov_b32 s48, 0x18000
	v_or_b32_e32 v76, 0x18000, v70
	v_mov_b32_e32 v77, v69
	s_movk_i32 s49, 0x800
	v_add_u32_e32 v85, v35, v36
	s_mov_b32 s50, s97
	s_mov_b32 s3, s97
	s_waitcnt vmcnt(0)
	s_branch .LBB0_39

; __device__ __forceinline__ TItem t_decode(const Ptrs& P, int it, int lane) {
;     ...
;     r -= 2 * I_A + I_O;
;     { const int nb = r % (NIN / 32), kb = r / (NIN / 32), vbase = 32 * nb;
;         t.N = NIN; t.ldk = D; t.src = P.w_in + (size_t)(64 * kb + r8) * NIN + w1_col_of(vbase + c4);
; __device__ __forceinline__ void p0_prologue(const Ptrs& P, LAS unsigned char* lds, int vcu, int G, int tid) {
;     ...
;         for (int it = gw; it < NITEMS; it += NGW) {
;             const int nit = it + NGW; const bool has_n = nit < NITEMS;
;             f32x4 nv[8];
;             const TItem nxt = t_decode(P, has_n ? nit : it, lane); t_load(nxt, nv);
.LBB0_39:
	s_mov_b32 s20, s50
	s_add_i32 s50, s50, s0
	s_cmp_gt_i32 s50, 0xffff
	s_cselect_b64 s[22:23], -1, 0
	s_cmp_lt_i32 s50, 0x10000
	s_cselect_b32 s53, s50, s20
	s_cmpk_gt_i32 s53, 0x3fff
	s_cbranch_scc1 .Lp0t_b_big
	s_and_b32 s94, s53, 7
	s_lshl_b32 s94, s94, 7
	s_bfe_u32 s95, s53, 0x70003
	s_and_b32 s53, s53, 0xfffffc00
	s_or_b32 s53, s53, s94
	s_or_b32 s53, s53, s95
	s_branch .Lp0t_b_done
.Lp0t_b_big:
	s_add_i32 s94, s53, 0xffffc000
	s_lshr_b32 s95, s94, 11
	s_mul_hi_u32 s95, s95, 0xaaaaaaab
	s_lshr_b32 s95, s95, 1
	s_mul_i32 s95, s95, 0x1800
	s_sub_i32 s94, s94, s95
	s_sub_i32 s53, s53, s94
	s_and_b32 s95, s94, 7
	s_mul_i32 s95, s95, 0x300
	s_lshr_b32 s94, s94, 3
	s_add_i32 s53, s53, s95
	s_add_i32 s53, s53, s94
.Lp0t_b_done:
	s_cmpk_gt_i32 s53, 0x3fff
	s_cbranch_scc0 .LBB0_52
	s_add_i32 s20, s53, 0xffffc000
	s_mul_hi_u32 s24, s20, 0xaaaaaaab
	s_lshr_b32 s29, s24, 9
	s_mul_i32 s24, s29, 0x300
	s_sub_i32 s28, s20, s24
	s_lshl_b32 s20, s28, 5
	s_cmpk_gt_u32 s28, 0x1ff
	s_cselect_b64 s[24:25], -1, 0
	s_mov_b64 s[26:27], -1
	s_and_b64 vcc, exec, s[24:25]
	s_cbranch_vccz .LBB0_42
	s_lshl_b32 s26, s28, 10
	s_and_b32 s26, s26, 0x1000
	s_lshl_b32 s27, s28, 4
	s_and_b32 s52, s20, 0x60
	s_and_b32 s27, s27, 0x3f80
	s_or_b32 s26, s52, s26
	s_add_i32 s26, s26, s27
	v_add_u32_e32 v68, s26, v83
	s_mov_b64 s[26:27], 0
